# row passes: nt hint on the y row loads only (last use), normalized-row loads unchanged
# baseline (speedup 1.0000x reference)
.LBB0_520:
	s_cmp_lt_i32 s88, 4
	s_cselect_b64 s[0:1], -1, 0
	s_and_b64 s[6:7], s[0:1], s[2:3]
	s_andn2_b64 vcc, exec, s[6:7]
	s_cbranch_vccnz .LBB0_526
	s_lshl_b32 s2, s66, 3
	s_lshl_b32 s0, s66, 7
	s_and_b32 s0, s0, 0xfffff000
	s_and_b32 s1, s2, 0xf8
	s_add_i32 s3, s0, 0x1000
	s_or_b32 s4, s0, s1
	s_cmpk_eq_i32 s68, 0x100
	s_cselect_b64 s[8:9], -1, 0
	s_and_b64 s[0:1], s[8:9], exec
	s_cselect_b32 s2, s4, s2
	s_cselect_b32 s12, s3, 0x8000
	s_add_i32 s13, s2, s96
	s_cmp_ge_i32 s13, s12
	s_cbranch_scc1 .LBB0_526
	v_lshlrev_b32_e32 v14, 4, v177
	global_load_dwordx4 v[2:5], v14, s[60:61]
	global_load_dwordx4 v[6:9], v14, s[60:61] offset:1024
	global_load_dwordx4 v[10:13], v14, s[60:61] offset:2048
	s_nop 0
	global_load_dwordx4 v[14:17], v14, s[60:61] offset:3072
	v_mbcnt_lo_u32_b32 v18, -1, 0
	v_mbcnt_hi_u32_b32 v18, -1, v18
	v_and_b32_e32 v19, 64, v18
	v_add_u32_e32 v19, 64, v19
	v_xor_b32_e32 v20, 1, v18
	v_cmp_lt_i32_e32 vcc, v20, v19
	v_readlane_b32 s4, v252, 2
	s_lshl_b32 s3, s68, 3
	v_cndmask_b32_e32 v20, v18, v20, vcc
	v_lshlrev_b32_e32 v26, 2, v20
	v_xor_b32_e32 v20, 2, v18
	v_cmp_lt_i32_e32 vcc, v20, v19
	v_readlane_b32 s5, v252, 3
	s_and_b64 s[0:1], s[8:9], exec
	v_cndmask_b32_e32 v20, v18, v20, vcc
	v_lshlrev_b32_e32 v27, 2, v20
	v_xor_b32_e32 v20, 4, v18
	v_cmp_lt_i32_e32 vcc, v20, v19
	s_cselect_b32 s14, 0x100, s3
	s_lshl_b32 s3, s66, 8
	v_cndmask_b32_e32 v20, v18, v20, vcc
	v_lshlrev_b32_e32 v28, 2, v20
	v_xor_b32_e32 v20, 8, v18
	v_cmp_lt_i32_e32 vcc, v20, v19
	s_and_b32 s3, s3, 0xffffe000
	s_add_i32 s3, s96, s3
	v_cndmask_b32_e32 v20, v18, v20, vcc
	v_lshlrev_b32_e32 v29, 2, v20
	v_xor_b32_e32 v20, 16, v18
	v_cmp_lt_i32_e32 vcc, v20, v19
	v_cmp_eq_u32_e64 s[0:1], 0, v177
	s_mov_b32 s16, 0xffff0000
	v_cndmask_b32_e32 v20, v18, v20, vcc
	v_lshlrev_b32_e32 v30, 2, v20
	v_xor_b32_e32 v20, 32, v18
	v_cmp_lt_i32_e32 vcc, v20, v19
	v_mov_b32_e32 v19, 0
	v_mov_b32_e32 v32, 0x358637bd
	v_cndmask_b32_e32 v18, v18, v20, vcc
	v_lshlrev_b32_e32 v31, 2, v18
	v_lshlrev_b32_e32 v18, 3, v177
	v_lshl_add_u64 v[20:21], s[4:5], 0, v[18:19]
	v_readlane_b32 s4, v253, 52
	v_readlane_b32 s5, v253, 53
	s_mov_b32 s17, 0xf800000
	v_mov_b32_e32 v33, 0x260
	v_lshl_add_u64 v[22:23], s[4:5], 0, v[18:19]
	s_and_b32 s4, s66, 31
	s_lshl_b32 s4, s4, 4
	s_add_i32 s3, s3, s4
	s_sub_i32 s2, s3, s2
	s_add_i32 s15, s2, 0xf00
	s_movk_i32 s18, 0x7fff
	s_and_b64 s[2:3], s[8:9], exec
	s_cselect_b32 s2, s15, s13
	s_ashr_i32 s3, s2, 31
	s_lshl_b64 s[4:5], s[2:3], 11
	v_lshl_add_u64 v[98:99], v[20:21], 0, s[4:5]
	v_lshl_add_u64 v[100:101], v[22:23], 0, s[4:5]
	s_lshl_b64 s[2:3], s[2:3], 2
	s_add_u32 s2, s75, s2
	s_addc_u32 s3, s69, s3
	global_load_dwordx2 v[80:81], v[98:99], off nt
	global_load_dwordx2 v[82:83], v[98:99], off offset:512 nt
	global_load_dwordx2 v[84:85], v[98:99], off offset:1024 nt
	global_load_dwordx2 v[86:87], v[98:99], off offset:1536 nt
	global_load_dwordx2 v[88:89], v[100:101], off
	global_load_dwordx2 v[90:91], v[100:101], off offset:512
	global_load_dwordx2 v[92:93], v[100:101], off offset:1024
	global_load_dwordx2 v[94:95], v[100:101], off offset:1536
	global_load_dword v96, v19, s[2:3]
	s_waitcnt vmcnt(0)
	s_branch .Lrp1_body

.Lrp1_body:
	v_mov_b32_e32 v34, v80
	v_mov_b32_e32 v35, v81
	v_mov_b32_e32 v36, v82
	v_mov_b32_e32 v37, v83
	v_mov_b32_e32 v38, v84
	v_mov_b32_e32 v39, v85
	v_mov_b32_e32 v40, v86
	v_mov_b32_e32 v41, v87
	v_mov_b32_e32 v42, v88
	v_mov_b32_e32 v43, v89
	v_mov_b32_e32 v44, v90
	v_mov_b32_e32 v45, v91
	v_mov_b32_e32 v46, v92
	v_mov_b32_e32 v47, v93
	v_mov_b32_e32 v48, v94
	v_mov_b32_e32 v49, v95
	v_mov_b32_e32 v18, v96
	s_and_b64 s[2:3], s[8:9], exec
	s_cselect_b32 s2, s15, s13
	s_ashr_i32 s3, s2, 31
	s_lshl_b64 s[4:5], s[2:3], 11
	s_lshl_b64 s[2:3], s[2:3], 2
	s_add_u32 s10, s75, s2
	v_lshl_add_u64 v[24:25], v[22:23], 0, s[4:5]
	s_addc_u32 s11, s69, s3
	s_add_i32 s2, s13, s14
	s_cmp_lt_i32 s2, s12
	s_cbranch_scc0 .Lrp1_skip
	s_sub_i32 s3, s15, s14
	s_and_b64 s[4:5], s[8:9], exec
	s_cselect_b32 s2, s3, s2
	s_ashr_i32 s3, s2, 31
	s_lshl_b64 s[4:5], s[2:3], 11
	v_lshl_add_u64 v[98:99], v[20:21], 0, s[4:5]
	v_lshl_add_u64 v[100:101], v[22:23], 0, s[4:5]
	s_lshl_b64 s[2:3], s[2:3], 2
	s_add_u32 s2, s75, s2
	s_addc_u32 s3, s69, s3
	global_load_dwordx2 v[80:81], v[98:99], off nt
	global_load_dwordx2 v[82:83], v[98:99], off offset:512 nt
	global_load_dwordx2 v[84:85], v[98:99], off offset:1024 nt
	global_load_dwordx2 v[86:87], v[98:99], off offset:1536 nt
	global_load_dwordx2 v[88:89], v[100:101], off
	global_load_dwordx2 v[90:91], v[100:101], off offset:512
	global_load_dwordx2 v[92:93], v[100:101], off offset:1024
	global_load_dwordx2 v[94:95], v[100:101], off offset:1536
	global_load_dword v96, v19, s[2:3]

.LBB0_1123:
	s_cmp_lt_i32 s88, 10
	s_cselect_b64 s[0:1], -1, 0
	s_and_b64 s[6:7], s[0:1], s[2:3]
	s_andn2_b64 vcc, exec, s[6:7]
	s_cbranch_vccnz .LBB0_1140
	s_lshl_b32 s2, s66, 3
	s_lshl_b32 s0, s66, 7
	s_and_b32 s0, s0, 0xfffff000
	s_and_b32 s1, s2, 0xf8
	s_add_i32 s3, s0, 0x1000
	s_or_b32 s4, s0, s1
	s_cmpk_eq_i32 s68, 0x100
	s_cselect_b64 s[8:9], -1, 0
	s_and_b64 s[0:1], s[8:9], exec
	s_cselect_b32 s2, s4, s2
	s_cselect_b32 s12, s3, 0x8000
	s_add_i32 s13, s2, s96
	s_cmp_ge_i32 s13, s12
	s_cbranch_scc1 .LBB0_1129
	v_readlane_b32 s36, v253, 20
	v_lshlrev_b32_e32 v1, 4, v177
	v_readlane_b32 s50, v253, 34
	v_readlane_b32 s51, v253, 35
	s_nop 4
	global_load_dwordx4 v[2:5], v1, s[50:51]
	global_load_dwordx4 v[6:9], v1, s[50:51] offset:1024
	global_load_dwordx4 v[10:13], v1, s[50:51] offset:2048
	global_load_dwordx4 v[14:17], v1, s[50:51] offset:3072
	v_mbcnt_lo_u32_b32 v1, -1, 0
	v_mbcnt_hi_u32_b32 v18, -1, v1
	v_and_b32_e32 v1, 64, v18
	v_add_u32_e32 v19, 64, v1
	v_xor_b32_e32 v1, 1, v18
	v_cmp_lt_i32_e32 vcc, v1, v19
	v_xor_b32_e32 v20, 2, v18
	v_readlane_b32 s4, v252, 2
	v_cndmask_b32_e32 v1, v18, v1, vcc
	v_cmp_lt_i32_e32 vcc, v20, v19
	s_lshl_b32 s3, s68, 3
	v_readlane_b32 s5, v252, 3
	v_cndmask_b32_e32 v20, v18, v20, vcc
	v_lshlrev_b32_e32 v26, 2, v20
	v_xor_b32_e32 v20, 4, v18
	v_cmp_lt_i32_e32 vcc, v20, v19
	s_mov_b64 s[14:15], s[50:51]
	s_and_b64 s[0:1], s[8:9], exec
	v_cndmask_b32_e32 v20, v18, v20, vcc
	v_lshlrev_b32_e32 v27, 2, v20
	v_xor_b32_e32 v20, 8, v18
	v_cmp_lt_i32_e32 vcc, v20, v19
	s_cselect_b32 s14, 0x100, s3
	s_lshl_b32 s3, s66, 8
	v_cndmask_b32_e32 v20, v18, v20, vcc
	v_lshlrev_b32_e32 v28, 2, v20
	v_xor_b32_e32 v20, 16, v18
	v_cmp_lt_i32_e32 vcc, v20, v19
	s_and_b32 s3, s3, 0xffffe000
	s_add_i32 s3, s96, s3
	v_cndmask_b32_e32 v20, v18, v20, vcc
	v_lshlrev_b32_e32 v29, 2, v20
	v_xor_b32_e32 v20, 32, v18
	v_cmp_lt_i32_e32 vcc, v20, v19
	v_mov_b32_e32 v19, 0
	v_lshlrev_b32_e32 v1, 2, v1
	v_cndmask_b32_e32 v18, v18, v20, vcc
	v_lshlrev_b32_e32 v30, 2, v18
	v_lshlrev_b32_e32 v18, 3, v177
	v_lshl_add_u64 v[20:21], s[4:5], 0, v[18:19]
	v_readlane_b32 s4, v253, 52
	v_readlane_b32 s5, v253, 53
	v_cmp_eq_u32_e64 s[0:1], 0, v177
	s_mov_b32 s16, 0xffff0000
	s_waitcnt vmcnt(0)
	v_lshl_add_u64 v[22:23], s[4:5], 0, v[18:19]
	s_and_b32 s4, s66, 31
	s_lshl_b32 s4, s4, 4
	s_add_i32 s3, s3, s4
	s_sub_i32 s2, s3, s2
	s_add_i32 s15, s2, 0xf00
	v_mov_b32_e32 v31, 0x358637bd
	s_mov_b32 s17, 0xf800000
	v_mov_b32_e32 v32, 0x260
	s_movk_i32 s18, 0x7fff
	v_readlane_b32 s37, v253, 21
	v_readlane_b32 s38, v253, 22
	v_readlane_b32 s39, v253, 23
	v_readlane_b32 s40, v253, 24
	v_readlane_b32 s41, v253, 25
	v_readlane_b32 s42, v253, 26
	v_readlane_b32 s43, v253, 27
	v_readlane_b32 s44, v253, 28
	v_readlane_b32 s45, v253, 29
	v_readlane_b32 s46, v253, 30
	v_readlane_b32 s47, v253, 31
	v_readlane_b32 s48, v253, 32
	v_readlane_b32 s49, v253, 33
	s_and_b64 s[2:3], s[8:9], exec
	s_cselect_b32 s2, s15, s13
	s_ashr_i32 s3, s2, 31
	s_lshl_b64 s[4:5], s[2:3], 11
	v_lshl_add_u64 v[98:99], v[20:21], 0, s[4:5]
	v_lshl_add_u64 v[100:101], v[22:23], 0, s[4:5]
	s_lshl_b64 s[2:3], s[2:3], 2
	s_add_u32 s2, s75, s2
	s_addc_u32 s3, s69, s3
	global_load_dwordx2 v[80:81], v[98:99], off nt
	global_load_dwordx2 v[82:83], v[98:99], off offset:512 nt
	global_load_dwordx2 v[84:85], v[98:99], off offset:1024 nt
	global_load_dwordx2 v[86:87], v[98:99], off offset:1536 nt
	global_load_dwordx2 v[88:89], v[100:101], off
	global_load_dwordx2 v[90:91], v[100:101], off offset:512
	global_load_dwordx2 v[92:93], v[100:101], off offset:1024
	global_load_dwordx2 v[94:95], v[100:101], off offset:1536
	global_load_dword v96, v19, s[2:3]
	s_waitcnt vmcnt(0)
	s_branch .Lrp2_body

.LBB0_1264:
	s_cmp_lt_i32 s88, 13
	s_cselect_b64 s[0:1], -1, 0
	s_and_b64 s[6:7], s[0:1], s[2:3]
	s_andn2_b64 vcc, exec, s[6:7]
	s_cbranch_vccnz .LBB0_1274
	s_lshl_b32 s12, s66, 3
	s_lshl_b32 s0, s66, 7
	s_and_b32 s0, s0, 0xfffff000
	s_and_b32 s1, s12, 0xf8
	s_add_i32 s2, s0, 0x1000
	s_or_b32 s3, s0, s1
	s_cmpk_eq_i32 s68, 0x100
	s_cselect_b64 s[8:9], -1, 0
	s_and_b64 s[0:1], s[8:9], exec
	s_cselect_b32 s13, s2, 0x8000
	s_cselect_b32 s2, s3, s12
	s_add_i32 s14, s2, s96
	s_cmp_ge_i32 s14, s13
	v_mov_b32_e32 v19, 0
	s_cbranch_scc1 .LBB0_1270
	v_lshlrev_b32_e32 v1, 4, v177
	global_load_dwordx4 v[2:5], v1, s[26:27]
	global_load_dwordx4 v[6:9], v1, s[26:27] offset:1024
	global_load_dwordx4 v[10:13], v1, s[26:27] offset:2048
	global_load_dwordx4 v[14:17], v1, s[26:27] offset:3072
	v_mbcnt_lo_u32_b32 v1, -1, 0
	v_mbcnt_hi_u32_b32 v18, -1, v1
	v_and_b32_e32 v1, 64, v18
	v_add_u32_e32 v20, 64, v1
	v_xor_b32_e32 v1, 1, v18
	v_cmp_lt_i32_e32 vcc, v1, v20
	v_xor_b32_e32 v21, 2, v18
	v_readlane_b32 s4, v252, 2
	v_cndmask_b32_e32 v1, v18, v1, vcc
	v_cmp_lt_i32_e32 vcc, v21, v20
	s_lshl_b32 s3, s68, 3
	v_readlane_b32 s5, v252, 3
	v_cndmask_b32_e32 v21, v18, v21, vcc
	v_lshlrev_b32_e32 v26, 2, v21
	v_xor_b32_e32 v21, 4, v18
	v_cmp_lt_i32_e32 vcc, v21, v20
	s_and_b64 s[0:1], s[8:9], exec
	s_cselect_b32 s15, 0x100, s3
	v_cndmask_b32_e32 v21, v18, v21, vcc
	v_lshlrev_b32_e32 v27, 2, v21
	v_xor_b32_e32 v21, 8, v18
	v_cmp_lt_i32_e32 vcc, v21, v20
	s_lshl_b32 s3, s66, 8
	s_and_b32 s3, s3, 0xffffe000
	v_cndmask_b32_e32 v21, v18, v21, vcc
	v_lshlrev_b32_e32 v28, 2, v21
	v_xor_b32_e32 v21, 16, v18
	v_cmp_lt_i32_e32 vcc, v21, v20
	s_add_i32 s3, s96, s3
	v_lshlrev_b32_e32 v1, 2, v1
	v_cndmask_b32_e32 v21, v18, v21, vcc
	v_lshlrev_b32_e32 v29, 2, v21
	v_xor_b32_e32 v21, 32, v18
	v_cmp_lt_i32_e32 vcc, v21, v20
	v_cmp_eq_u32_e64 s[0:1], 0, v177
	s_mov_b32 s17, 0xffff0000
	v_cndmask_b32_e32 v18, v18, v21, vcc
	v_lshlrev_b32_e32 v30, 2, v18
	v_lshlrev_b32_e32 v18, 3, v177
	v_lshl_add_u64 v[20:21], s[4:5], 0, v[18:19]
	v_readlane_b32 s4, v253, 52
	v_readlane_b32 s5, v253, 53
	v_mov_b32_e32 v31, 0x358637bd
	s_mov_b32 s18, 0xf800000
	s_waitcnt vmcnt(0)
	v_lshl_add_u64 v[22:23], s[4:5], 0, v[18:19]
	s_and_b32 s4, s66, 31
	s_lshl_b32 s4, s4, 4
	s_add_i32 s3, s3, s4
	s_sub_i32 s2, s3, s2
	s_add_i32 s16, s2, 0xf00
	v_mov_b32_e32 v32, 0x260
	s_movk_i32 s19, 0x7fff
	s_and_b64 s[2:3], s[8:9], exec
	s_cselect_b32 s2, s16, s14
	s_ashr_i32 s3, s2, 31
	s_lshl_b64 s[4:5], s[2:3], 11
	v_lshl_add_u64 v[98:99], v[20:21], 0, s[4:5]
	v_lshl_add_u64 v[100:101], v[22:23], 0, s[4:5]
	s_lshl_b64 s[2:3], s[2:3], 2
	s_add_u32 s2, s75, s2
	s_addc_u32 s3, s69, s3
	global_load_dwordx2 v[80:81], v[98:99], off nt
	global_load_dwordx2 v[82:83], v[98:99], off offset:512 nt
	global_load_dwordx2 v[84:85], v[98:99], off offset:1024 nt
	global_load_dwordx2 v[86:87], v[98:99], off offset:1536 nt
	global_load_dwordx2 v[88:89], v[100:101], off
	global_load_dwordx2 v[90:91], v[100:101], off offset:512
	global_load_dwordx2 v[92:93], v[100:101], off offset:1024
	global_load_dwordx2 v[94:95], v[100:101], off offset:1536
	global_load_dword v96, v19, s[2:3]
	s_waitcnt vmcnt(0)
	s_branch .Lrp3_body

.Lrp3_body:
	v_mov_b32_e32 v34, v80
	v_mov_b32_e32 v35, v81
	v_mov_b32_e32 v36, v82
	v_mov_b32_e32 v37, v83
	v_mov_b32_e32 v38, v84
	v_mov_b32_e32 v39, v85
	v_mov_b32_e32 v40, v86
	v_mov_b32_e32 v41, v87
	v_mov_b32_e32 v42, v88
	v_mov_b32_e32 v43, v89
	v_mov_b32_e32 v44, v90
	v_mov_b32_e32 v45, v91
	v_mov_b32_e32 v46, v92
	v_mov_b32_e32 v47, v93
	v_mov_b32_e32 v48, v94
	v_mov_b32_e32 v49, v95
	v_mov_b32_e32 v18, v96
	s_and_b64 s[2:3], s[8:9], exec
	s_cselect_b32 s2, s16, s14
	s_ashr_i32 s3, s2, 31
	s_lshl_b64 s[4:5], s[2:3], 11
	s_lshl_b64 s[2:3], s[2:3], 2
	s_add_u32 s10, s75, s2
	v_lshl_add_u64 v[24:25], v[22:23], 0, s[4:5]
	s_addc_u32 s11, s69, s3
	s_add_i32 s2, s14, s15
	s_cmp_lt_i32 s2, s13
	s_cbranch_scc0 .Lrp3_skip
	s_sub_i32 s3, s16, s15
	s_and_b64 s[4:5], s[8:9], exec
	s_cselect_b32 s2, s3, s2
	s_ashr_i32 s3, s2, 31
	s_lshl_b64 s[4:5], s[2:3], 11
	v_lshl_add_u64 v[98:99], v[20:21], 0, s[4:5]
	v_lshl_add_u64 v[100:101], v[22:23], 0, s[4:5]
	s_lshl_b64 s[2:3], s[2:3], 2
	s_add_u32 s2, s75, s2
	s_addc_u32 s3, s69, s3
	global_load_dwordx2 v[80:81], v[98:99], off nt
	global_load_dwordx2 v[82:83], v[98:99], off offset:512 nt
	global_load_dwordx2 v[84:85], v[98:99], off offset:1024 nt
	global_load_dwordx2 v[86:87], v[98:99], off offset:1536 nt
	global_load_dwordx2 v[88:89], v[100:101], off
	global_load_dwordx2 v[90:91], v[100:101], off offset:512
	global_load_dwordx2 v[92:93], v[100:101], off offset:1024
	global_load_dwordx2 v[94:95], v[100:101], off offset:1536
	global_load_dword v96, v19, s[2:3]

.LBB0_1478:
	s_lshl_b32 s2, s66, 3
	s_lshl_b32 s0, s66, 7
	s_and_b32 s0, s0, 0xfffff000
	s_and_b32 s1, s2, 0xf8
	s_add_i32 s3, s0, 0x1000
	s_or_b32 s8, s0, s1
	s_cmpk_eq_i32 s68, 0x100
	s_cselect_b64 s[6:7], -1, 0
	s_and_b64 s[0:1], s[6:7], exec
	s_cselect_b32 s2, s8, s2
	s_cselect_b32 s12, s3, 0x8000
	s_add_i32 s13, s2, s96
	s_cmp_lt_i32 s13, s12
	s_cbranch_scc0 .LBB0_1487
	v_mbcnt_lo_u32_b32 v32, -1, 0
	v_mbcnt_hi_u32_b32 v32, -1, v32
	v_and_b32_e32 v33, 64, v32
	v_add_u32_e32 v33, 64, v33
	v_xor_b32_e32 v34, 1, v32
	v_cmp_lt_i32_e32 vcc, v34, v33
	v_readlane_b32 s8, v252, 2
	s_lshl_b32 s3, s68, 3
	v_cndmask_b32_e32 v34, v32, v34, vcc
	v_lshlrev_b32_e32 v58, 2, v34
	v_xor_b32_e32 v34, 2, v32
	v_cmp_lt_i32_e32 vcc, v34, v33
	v_readlane_b32 s9, v252, 3
	s_and_b64 s[0:1], s[6:7], exec
	v_cndmask_b32_e32 v34, v32, v34, vcc
	v_lshlrev_b32_e32 v59, 2, v34
	v_xor_b32_e32 v34, 4, v32
	v_cmp_lt_i32_e32 vcc, v34, v33
	s_cselect_b32 s14, 0x100, s3
	s_lshl_b32 s3, s66, 8
	v_cndmask_b32_e32 v34, v32, v34, vcc
	v_lshlrev_b32_e32 v60, 2, v34
	v_xor_b32_e32 v34, 8, v32
	v_cmp_lt_i32_e32 vcc, v34, v33
	s_and_b32 s3, s3, 0xffffe000
	s_add_i32 s3, s96, s3
	v_cndmask_b32_e32 v34, v32, v34, vcc
	v_lshlrev_b32_e32 v61, 2, v34
	v_xor_b32_e32 v34, 16, v32
	v_cmp_lt_i32_e32 vcc, v34, v33
	v_cmp_eq_u32_e64 s[0:1], 0, v177
	s_mov_b32 s16, 0xffff0000
	v_cndmask_b32_e32 v34, v32, v34, vcc
	v_lshlrev_b32_e32 v62, 2, v34
	v_xor_b32_e32 v34, 32, v32
	v_cmp_lt_i32_e32 vcc, v34, v33
	v_mov_b32_e32 v33, 0
	v_mov_b32_e32 v39, v33
	v_cndmask_b32_e32 v32, v32, v34, vcc
	v_lshlrev_b32_e32 v63, 2, v32
	v_lshlrev_b32_e32 v32, 3, v177
	v_lshl_add_u64 v[34:35], s[8:9], 0, v[32:33]
	v_readlane_b32 s8, v253, 52
	v_readlane_b32 s9, v253, 53
	v_lshl_add_u64 v[38:39], s[76:77], 0, v[38:39]
	v_mov_b32_e32 v64, 0x358637bd
	v_lshl_add_u64 v[36:37], s[8:9], 0, v[32:33]
	s_and_b32 s8, s66, 31
	s_lshl_b32 s8, s8, 4
	s_add_i32 s3, s3, s8
	s_sub_i32 s2, s3, s2
	s_add_i32 s15, s2, 0xf00
	s_mov_b32 s17, 0xf800000
	v_mov_b32_e32 v65, 0x260
	s_movk_i32 s18, 0x7fff
	s_and_b64 s[2:3], s[6:7], exec
	s_cselect_b32 s2, s15, s13
	s_ashr_i32 s3, s2, 31
	s_lshl_b64 vcc, s[2:3], 11
	v_lshl_add_u64 v[118:119], v[34:35], 0, vcc
	v_lshl_add_u64 v[120:121], v[36:37], 0, vcc
	s_lshl_b64 s[2:3], s[2:3], 2
	s_add_u32 s2, s75, s2
	s_addc_u32 s3, s69, s3
	global_load_dwordx2 v[100:101], v[118:119], off nt
	global_load_dwordx2 v[102:103], v[118:119], off offset:512 nt
	global_load_dwordx2 v[104:105], v[118:119], off offset:1024 nt
	global_load_dwordx2 v[106:107], v[118:119], off offset:1536 nt
	global_load_dwordx2 v[108:109], v[120:121], off
	global_load_dwordx2 v[110:111], v[120:121], off offset:512
	global_load_dwordx2 v[112:113], v[120:121], off offset:1024
	global_load_dwordx2 v[114:115], v[120:121], off offset:1536
	global_load_dword v116, v33, s[2:3]
	s_waitcnt vmcnt(0)
	s_branch .Lrp4_body

.Lrp4_body:
	v_mov_b32_e32 v42, v100
	v_mov_b32_e32 v43, v101
	v_mov_b32_e32 v44, v102
	v_mov_b32_e32 v45, v103
	v_mov_b32_e32 v46, v104
	v_mov_b32_e32 v47, v105
	v_mov_b32_e32 v48, v106
	v_mov_b32_e32 v49, v107
	v_mov_b32_e32 v50, v108
	v_mov_b32_e32 v51, v109
	v_mov_b32_e32 v52, v110
	v_mov_b32_e32 v53, v111
	v_mov_b32_e32 v54, v112
	v_mov_b32_e32 v55, v113
	v_mov_b32_e32 v56, v114
	v_mov_b32_e32 v57, v115
	v_mov_b32_e32 v32, v116
	s_and_b64 s[2:3], s[6:7], exec
	s_cselect_b32 s10, s15, s13
	s_ashr_i32 s11, s10, 31
	s_lshl_b64 s[2:3], s[10:11], 11
	v_lshl_add_u64 v[40:41], v[36:37], 0, s[2:3]
	s_lshl_b64 s[2:3], s[10:11], 2
	s_add_u32 s8, s75, s2
	s_addc_u32 s9, s69, s3
	s_add_i32 s2, s13, s14
	s_cmp_lt_i32 s2, s12
	s_cbranch_scc0 .Lrp4_skip
	s_sub_i32 s3, s15, s14
	s_and_b64 vcc, s[6:7], exec
	s_cselect_b32 s2, s3, s2
	s_ashr_i32 s3, s2, 31
	s_lshl_b64 vcc, s[2:3], 11
	v_lshl_add_u64 v[118:119], v[34:35], 0, vcc
	v_lshl_add_u64 v[120:121], v[36:37], 0, vcc
	s_lshl_b64 s[2:3], s[2:3], 2
	s_add_u32 s2, s75, s2
	s_addc_u32 s3, s69, s3
	global_load_dwordx2 v[100:101], v[118:119], off nt
	global_load_dwordx2 v[102:103], v[118:119], off offset:512 nt
	global_load_dwordx2 v[104:105], v[118:119], off offset:1024 nt
	global_load_dwordx2 v[106:107], v[118:119], off offset:1536 nt
	global_load_dwordx2 v[108:109], v[120:121], off
	global_load_dwordx2 v[110:111], v[120:121], off offset:512
	global_load_dwordx2 v[112:113], v[120:121], off offset:1024
	global_load_dwordx2 v[114:115], v[120:121], off offset:1536
	global_load_dword v116, v33, s[2:3]
